# MLA: staging LDS writes wait per load in load order (V first) instead of one vmcnt(0) before all five
# speedup vs baseline: 1.0087x; 1.0087x over previous
.Lmla_x_cont0:
	v_exp_f32_e32 v116, v116
	v_exp_f32_e32 v117, v117
	v_exp_f32_e32 v118, v118
	v_exp_f32_e32 v119, v119
	v_exp_f32_e32 v132, v132
	v_exp_f32_e32 v133, v133
	v_exp_f32_e32 v134, v134
	v_exp_f32_e32 v135, v135
	s_waitcnt lgkmcnt(8)
	v_exp_f32_e32 v120, v120
	v_mfma_f32_16x16x32_bf16 v[176:179], v[4:7], v[8:11], v[108:111]
	v_exp_f32_e32 v121, v121
	v_mfma_f32_16x16x32_bf16 v[192:195], v[4:7], v[40:43], v[112:115]
	v_exp_f32_e32 v122, v122
	v_mfma_f32_16x16x32_bf16 v[176:179], v[12:15], v[32:35], v[176:179]
	v_exp_f32_e32 v123, v123
	v_mfma_f32_16x16x32_bf16 v[192:195], v[12:15], v[44:47], v[192:195]
	v_exp_f32_e32 v136, v136
	v_mfma_f32_16x16x32_bf16 v[176:179], v[20:23], v[36:39], v[176:179]
	v_exp_f32_e32 v137, v137
	v_mfma_f32_16x16x32_bf16 v[192:195], v[20:23], v[16:19], v[192:195]
	v_exp_f32_e32 v138, v138
	v_exp_f32_e32 v139, v139
	ds_read_b128 v[4:7], v175 offset:21504
	ds_read_b128 v[12:15], v175 offset:25600
	ds_read_b128 v[20:23], v175 offset:29696
	v_cvt_pk_bf16_f32 v116, v116, v117
	v_cvt_pk_bf16_f32 v117, v118, v119
	v_cvt_pk_bf16_f32 v118, v120, v121
	v_cvt_pk_bf16_f32 v119, v122, v123
	v_cvt_pk_bf16_f32 v132, v132, v133
	v_cvt_pk_bf16_f32 v133, v134, v135
	v_cvt_pk_bf16_f32 v134, v136, v137
	v_cvt_pk_bf16_f32 v135, v138, v139
	s_waitcnt lgkmcnt(0)
	v_exp_f32_e32 v124, v124
	v_mfma_f32_16x16x32_bf16 v[180:183], v[4:7], v[8:11], v[108:111]
	v_exp_f32_e32 v125, v125
	v_mfma_f32_16x16x32_bf16 v[196:199], v[4:7], v[40:43], v[112:115]
	v_exp_f32_e32 v126, v126
	v_mfma_f32_16x16x32_bf16 v[180:183], v[12:15], v[32:35], v[180:183]
	v_exp_f32_e32 v127, v127
	v_mfma_f32_16x16x32_bf16 v[196:199], v[12:15], v[44:47], v[196:199]
	v_exp_f32_e32 v140, v140
	v_mfma_f32_16x16x32_bf16 v[180:183], v[20:23], v[36:39], v[180:183]
	v_exp_f32_e32 v141, v141
	v_mfma_f32_16x16x32_bf16 v[196:199], v[20:23], v[16:19], v[196:199]
	v_exp_f32_e32 v142, v142
	v_exp_f32_e32 v143, v143
	ds_read_b128 v[4:7], v175 offset:22528
	ds_read_b128 v[12:15], v175 offset:26624
	ds_read_b128 v[20:23], v175 offset:30720
	ds_read_b64_tr_b16 v[208:209], v167 offset:16384
	ds_read_b64_tr_b16 v[210:211], v167 offset:18432
	ds_read_b64_tr_b16 v[240:241], v171 offset:16384
	ds_read_b64_tr_b16 v[242:243], v171 offset:18432
	ds_read_b64_tr_b16 v[252:253], v172 offset:16384
	ds_read_b64_tr_b16 v[254:255], v172 offset:18432
	s_setprio 0
	v_mfma_f32_16x16x32_bf16 v[104:107], v[248:251], v[116:119], v[104:107]
	v_exp_f32_e32 v128, v128
	v_mfma_f32_16x16x32_bf16 v[88:91], v[248:251], v[132:135], v[88:91]
	v_exp_f32_e32 v129, v129
	v_mfma_f32_16x16x32_bf16 v[100:103], v[24:27], v[116:119], v[100:103]
	v_exp_f32_e32 v130, v130
	v_mfma_f32_16x16x32_bf16 v[80:83], v[24:27], v[132:135], v[80:83]
	v_exp_f32_e32 v131, v131
	v_mfma_f32_16x16x32_bf16 v[96:99], v[28:31], v[116:119], v[96:99]
	v_exp_f32_e32 v144, v144
	v_mfma_f32_16x16x32_bf16 v[76:79], v[28:31], v[132:135], v[76:79]
	v_exp_f32_e32 v145, v145
	s_waitcnt lgkmcnt(6)
	v_mfma_f32_16x16x32_bf16 v[184:187], v[4:7], v[8:11], v[108:111]
	v_exp_f32_e32 v146, v146
	v_exp_f32_e32 v147, v147
	v_mfma_f32_16x16x32_bf16 v[200:203], v[4:7], v[40:43], v[112:115]
	s_nop 0
	v_cvt_pk_bf16_f32 v124, v124, v125
	v_mfma_f32_16x16x32_bf16 v[184:187], v[12:15], v[32:35], v[184:187]
	v_cvt_pk_bf16_f32 v125, v126, v127
	v_cvt_pk_bf16_f32 v126, v128, v129
	v_mfma_f32_16x16x32_bf16 v[200:203], v[12:15], v[44:47], v[200:203]
	v_cvt_pk_bf16_f32 v127, v130, v131
	v_cvt_pk_bf16_f32 v140, v140, v141
	v_mfma_f32_16x16x32_bf16 v[184:187], v[20:23], v[36:39], v[184:187]
	v_cvt_pk_bf16_f32 v141, v142, v143
	v_cvt_pk_bf16_f32 v142, v144, v145
	v_mfma_f32_16x16x32_bf16 v[200:203], v[20:23], v[16:19], v[200:203]
	v_cvt_pk_bf16_f32 v143, v146, v147
	ds_read_b128 v[4:7], v175 offset:23552
	ds_read_b128 v[12:15], v175 offset:27648
	ds_read_b128 v[20:23], v175 offset:31744
	ds_read_b64_tr_b16 v[24:25], v173 offset:16384
	ds_read_b64_tr_b16 v[26:27], v173 offset:18432
	v_mfma_f32_16x16x32_bf16 v[92:95], v[148:151], v[116:119], v[92:95]
	v_mfma_f32_16x16x32_bf16 v[72:75], v[148:151], v[132:135], v[72:75]
	v_mfma_f32_16x16x32_bf16 v[84:87], v[152:155], v[116:119], v[84:87]
	v_mfma_f32_16x16x32_bf16 v[68:71], v[152:155], v[132:135], v[68:71]
	s_waitcnt lgkmcnt(2)
	v_mfma_f32_16x16x32_bf16 v[188:191], v[4:7], v[8:11], v[108:111]
	s_waitcnt vmcnt(3)
	v_mfma_f32_16x16x32_bf16 v[204:207], v[4:7], v[40:43], v[112:115]
	ds_write_b128 v170, v[48:51] offset:32768
	v_mfma_f32_16x16x32_bf16 v[188:191], v[12:15], v[32:35], v[188:191]
	ds_write_b128 v170, v[64:67] offset:36864
	v_mfma_f32_16x16x32_bf16 v[204:207], v[12:15], v[44:47], v[204:207]
	s_waitcnt vmcnt(2)
	v_mfma_f32_16x16x32_bf16 v[188:191], v[20:23], v[36:39], v[188:191]
	ds_write_b128 v168, v[56:59] offset:0
	v_mfma_f32_16x16x32_bf16 v[204:207], v[20:23], v[16:19], v[204:207]
	s_waitcnt vmcnt(1)
	ds_write_b128 v168, v[60:63] offset:2048
	s_waitcnt vmcnt(0)
	ds_write_b128 v169, v[52:55] offset:8192
	v_mfma_f32_16x16x32_bf16 v[104:107], v[248:251], v[124:127], v[104:107]
	global_load_dwordx4 v[48:51], v[164:165], off offset:128
	s_mov_b64 s[0:1], 0x10000
	v_lshl_add_u64 v[212:213], v[164:165], 0, s[0:1]
	global_load_dwordx4 v[64:67], v[212:213], off offset:128
	v_mfma_f32_16x16x32_bf16 v[88:91], v[248:251], v[140:143], v[88:91]
	s_mov_b64 s[0:1], 0x20000
	v_lshl_add_u64 v[164:165], v[164:165], 0, s[0:1]
	global_load_dwordx4 v[56:59], v[164:165], off
	s_mov_b64 s[0:1], 0x10000
	v_mfma_f32_16x16x32_bf16 v[100:103], v[208:211], v[124:127], v[100:103]
	v_lshl_add_u64 v[212:213], v[164:165], 0, s[0:1]
	global_load_dwordx4 v[60:63], v[212:213], off
	global_load_dwordx4 v[52:55], v[160:161], off
	s_mov_b64 s[0:1], 0xe4000
	v_mfma_f32_16x16x32_bf16 v[80:83], v[208:211], v[140:143], v[80:83]
	v_lshl_add_u64 v[160:161], v[160:161], 0, s[0:1]
	v_max3_f32 v2, v176, v177, v178
	v_max3_f32 v3, v192, v193, v194
	v_max3_f32 v2, v2, v179, v180
	v_mfma_f32_16x16x32_bf16 v[96:99], v[240:243], v[124:127], v[96:99]
	v_max3_f32 v3, v3, v195, v196
	v_max3_f32 v2, v2, v181, v182
	v_max3_f32 v3, v3, v197, v198
	v_max3_f32 v2, v2, v183, v184
	v_mfma_f32_16x16x32_bf16 v[76:79], v[240:243], v[140:143], v[76:79]
	v_max3_f32 v3, v3, v199, v200
	v_max3_f32 v2, v2, v185, v186
	v_max3_f32 v3, v3, v201, v202
	v_max3_f32 v2, v2, v187, v188
	v_mfma_f32_16x16x32_bf16 v[92:95], v[252:255], v[124:127], v[92:95]
	v_max3_f32 v3, v3, v203, v204
	v_max3_f32 v2, v2, v189, v190
	v_max3_f32 v3, v3, v205, v206
	v_max3_f32 v2, v2, v191, v191
	v_mfma_f32_16x16x32_bf16 v[72:75], v[252:255], v[140:143], v[72:75]
	v_max3_f32 v3, v3, v207, v207
	s_waitcnt lgkmcnt(0)
	v_mfma_f32_16x16x32_bf16 v[84:87], v[24:27], v[124:127], v[84:87]
	v_mfma_f32_16x16x32_bf16 v[68:71], v[24:27], v[140:143], v[68:71]
	s_add_i32 s57, s57, 1
	s_cmp_lt_u32 s57, s44
	s_barrier
	s_setprio 2
	s_cbranch_scc0 .Lmla_x_done

.Lmla_x_cont1:
	v_exp_f32_e32 v176, v176
	v_exp_f32_e32 v177, v177
	v_exp_f32_e32 v178, v178
	v_exp_f32_e32 v179, v179
	v_exp_f32_e32 v192, v192
	v_exp_f32_e32 v193, v193
	v_exp_f32_e32 v194, v194
	v_exp_f32_e32 v195, v195
	s_waitcnt lgkmcnt(8)
	v_exp_f32_e32 v180, v180
	v_mfma_f32_16x16x32_bf16 v[116:119], v[4:7], v[8:11], v[108:111]
	v_exp_f32_e32 v181, v181
	v_mfma_f32_16x16x32_bf16 v[132:135], v[4:7], v[40:43], v[112:115]
	v_exp_f32_e32 v182, v182
	v_mfma_f32_16x16x32_bf16 v[116:119], v[12:15], v[32:35], v[116:119]
	v_exp_f32_e32 v183, v183
	v_mfma_f32_16x16x32_bf16 v[132:135], v[12:15], v[44:47], v[132:135]
	v_exp_f32_e32 v196, v196
	v_mfma_f32_16x16x32_bf16 v[116:119], v[20:23], v[36:39], v[116:119]
	v_exp_f32_e32 v197, v197
	v_mfma_f32_16x16x32_bf16 v[132:135], v[20:23], v[16:19], v[132:135]
	v_exp_f32_e32 v198, v198
	v_exp_f32_e32 v199, v199
	ds_read_b128 v[4:7], v175 offset:1024
	ds_read_b128 v[12:15], v175 offset:5120
	ds_read_b128 v[20:23], v175 offset:9216
	v_cvt_pk_bf16_f32 v176, v176, v177
	v_cvt_pk_bf16_f32 v177, v178, v179
	v_cvt_pk_bf16_f32 v178, v180, v181
	v_cvt_pk_bf16_f32 v179, v182, v183
	v_cvt_pk_bf16_f32 v192, v192, v193
	v_cvt_pk_bf16_f32 v193, v194, v195
	v_cvt_pk_bf16_f32 v194, v196, v197
	v_cvt_pk_bf16_f32 v195, v198, v199
	s_waitcnt lgkmcnt(0)
	v_exp_f32_e32 v184, v184
	v_mfma_f32_16x16x32_bf16 v[120:123], v[4:7], v[8:11], v[108:111]
	v_exp_f32_e32 v185, v185
	v_mfma_f32_16x16x32_bf16 v[136:139], v[4:7], v[40:43], v[112:115]
	v_exp_f32_e32 v186, v186
	v_mfma_f32_16x16x32_bf16 v[120:123], v[12:15], v[32:35], v[120:123]
	v_exp_f32_e32 v187, v187
	v_mfma_f32_16x16x32_bf16 v[136:139], v[12:15], v[44:47], v[136:139]
	v_exp_f32_e32 v200, v200
	v_mfma_f32_16x16x32_bf16 v[120:123], v[20:23], v[36:39], v[120:123]
	v_exp_f32_e32 v201, v201
	v_mfma_f32_16x16x32_bf16 v[136:139], v[20:23], v[16:19], v[136:139]
	v_exp_f32_e32 v202, v202
	v_exp_f32_e32 v203, v203
	ds_read_b128 v[4:7], v175 offset:2048
	ds_read_b128 v[12:15], v175 offset:6144
	ds_read_b128 v[20:23], v175 offset:10240
	ds_read_b64_tr_b16 v[208:209], v167 offset:36864
	ds_read_b64_tr_b16 v[210:211], v167 offset:38912
	ds_read_b64_tr_b16 v[240:241], v171 offset:36864
	ds_read_b64_tr_b16 v[242:243], v171 offset:38912
	ds_read_b64_tr_b16 v[252:253], v172 offset:36864
	ds_read_b64_tr_b16 v[254:255], v172 offset:38912
	s_setprio 0
	v_mfma_f32_16x16x32_bf16 v[104:107], v[248:251], v[176:179], v[104:107]
	v_exp_f32_e32 v188, v188
	v_mfma_f32_16x16x32_bf16 v[88:91], v[248:251], v[192:195], v[88:91]
	v_exp_f32_e32 v189, v189
	v_mfma_f32_16x16x32_bf16 v[100:103], v[24:27], v[176:179], v[100:103]
	v_exp_f32_e32 v190, v190
	v_mfma_f32_16x16x32_bf16 v[80:83], v[24:27], v[192:195], v[80:83]
	v_exp_f32_e32 v191, v191
	v_mfma_f32_16x16x32_bf16 v[96:99], v[28:31], v[176:179], v[96:99]
	v_exp_f32_e32 v204, v204
	v_mfma_f32_16x16x32_bf16 v[76:79], v[28:31], v[192:195], v[76:79]
	v_exp_f32_e32 v205, v205
	s_waitcnt lgkmcnt(6)
	v_mfma_f32_16x16x32_bf16 v[124:127], v[4:7], v[8:11], v[108:111]
	v_exp_f32_e32 v206, v206
	v_exp_f32_e32 v207, v207
	v_mfma_f32_16x16x32_bf16 v[140:143], v[4:7], v[40:43], v[112:115]
	s_nop 0
	v_cvt_pk_bf16_f32 v184, v184, v185
	v_mfma_f32_16x16x32_bf16 v[124:127], v[12:15], v[32:35], v[124:127]
	v_cvt_pk_bf16_f32 v185, v186, v187
	v_cvt_pk_bf16_f32 v186, v188, v189
	v_mfma_f32_16x16x32_bf16 v[140:143], v[12:15], v[44:47], v[140:143]
	v_cvt_pk_bf16_f32 v187, v190, v191
	v_cvt_pk_bf16_f32 v200, v200, v201
	v_mfma_f32_16x16x32_bf16 v[124:127], v[20:23], v[36:39], v[124:127]
	v_cvt_pk_bf16_f32 v201, v202, v203
	v_cvt_pk_bf16_f32 v202, v204, v205
	v_mfma_f32_16x16x32_bf16 v[140:143], v[20:23], v[16:19], v[140:143]
	v_cvt_pk_bf16_f32 v203, v206, v207
	ds_read_b128 v[4:7], v175 offset:3072
	ds_read_b128 v[12:15], v175 offset:7168
	ds_read_b128 v[20:23], v175 offset:11264
	ds_read_b64_tr_b16 v[24:25], v173 offset:36864
	ds_read_b64_tr_b16 v[26:27], v173 offset:38912
	v_mfma_f32_16x16x32_bf16 v[92:95], v[148:151], v[176:179], v[92:95]
	v_mfma_f32_16x16x32_bf16 v[72:75], v[148:151], v[192:195], v[72:75]
	v_mfma_f32_16x16x32_bf16 v[84:87], v[152:155], v[176:179], v[84:87]
	v_mfma_f32_16x16x32_bf16 v[68:71], v[152:155], v[192:195], v[68:71]
	s_waitcnt lgkmcnt(2)
	v_mfma_f32_16x16x32_bf16 v[128:131], v[4:7], v[8:11], v[108:111]
	s_waitcnt vmcnt(3)
	v_mfma_f32_16x16x32_bf16 v[144:147], v[4:7], v[40:43], v[112:115]
	ds_write_b128 v170, v[48:51] offset:12288
	v_mfma_f32_16x16x32_bf16 v[128:131], v[12:15], v[32:35], v[128:131]
	ds_write_b128 v170, v[64:67] offset:16384
	v_mfma_f32_16x16x32_bf16 v[144:147], v[12:15], v[44:47], v[144:147]
	s_waitcnt vmcnt(2)
	v_mfma_f32_16x16x32_bf16 v[128:131], v[20:23], v[36:39], v[128:131]
	ds_write_b128 v168, v[56:59] offset:20480
	v_mfma_f32_16x16x32_bf16 v[144:147], v[20:23], v[16:19], v[144:147]
	s_waitcnt vmcnt(1)
	ds_write_b128 v168, v[60:63] offset:22528
	s_waitcnt vmcnt(0)
	ds_write_b128 v169, v[52:55] offset:28672
	v_mfma_f32_16x16x32_bf16 v[104:107], v[248:251], v[184:187], v[104:107]
	global_load_dwordx4 v[48:51], v[164:165], off offset:128
	s_mov_b64 s[0:1], 0x10000
	v_lshl_add_u64 v[212:213], v[164:165], 0, s[0:1]
	global_load_dwordx4 v[64:67], v[212:213], off offset:128
	v_mfma_f32_16x16x32_bf16 v[88:91], v[248:251], v[200:203], v[88:91]
	s_mov_b64 s[0:1], 0x20000
	v_lshl_add_u64 v[164:165], v[164:165], 0, s[0:1]
	global_load_dwordx4 v[56:59], v[164:165], off
	s_mov_b64 s[0:1], 0x10000
	v_mfma_f32_16x16x32_bf16 v[100:103], v[208:211], v[184:187], v[100:103]
	v_lshl_add_u64 v[212:213], v[164:165], 0, s[0:1]
	global_load_dwordx4 v[60:63], v[212:213], off
	global_load_dwordx4 v[52:55], v[160:161], off
	s_mov_b64 s[0:1], 0xe4000
	v_mfma_f32_16x16x32_bf16 v[80:83], v[208:211], v[200:203], v[80:83]
	v_lshl_add_u64 v[160:161], v[160:161], 0, s[0:1]
	v_max3_f32 v2, v116, v117, v118
	v_max3_f32 v3, v132, v133, v134
	v_max3_f32 v2, v2, v119, v120
	v_mfma_f32_16x16x32_bf16 v[96:99], v[240:243], v[184:187], v[96:99]
	v_max3_f32 v3, v3, v135, v136
	v_max3_f32 v2, v2, v121, v122
	v_max3_f32 v3, v3, v137, v138
	v_max3_f32 v2, v2, v123, v124
	v_mfma_f32_16x16x32_bf16 v[76:79], v[240:243], v[200:203], v[76:79]
	v_max3_f32 v3, v3, v139, v140
	v_max3_f32 v2, v2, v125, v126
	v_max3_f32 v3, v3, v141, v142
	v_max3_f32 v2, v2, v127, v128
	v_mfma_f32_16x16x32_bf16 v[92:95], v[252:255], v[184:187], v[92:95]
	v_max3_f32 v3, v3, v143, v144
	v_max3_f32 v2, v2, v129, v130
	v_max3_f32 v3, v3, v145, v146
	v_max3_f32 v2, v2, v131, v131
	v_mfma_f32_16x16x32_bf16 v[72:75], v[252:255], v[200:203], v[72:75]
	v_max3_f32 v3, v3, v147, v147
	s_waitcnt lgkmcnt(0)
	v_mfma_f32_16x16x32_bf16 v[84:87], v[24:27], v[184:187], v[84:87]
	v_mfma_f32_16x16x32_bf16 v[68:71], v[24:27], v[200:203], v[68:71]
	s_add_i32 s57, s57, 1
	s_cmp_lt_u32 s57, s44
	s_barrier
	s_setprio 2
	s_cbranch_scc1 .Lmla_x_body0
